# prep phase: the four item kinds interleaved over the work queue (index remap) so store-bound and compute-bound items overlap, on top of cprep load hoisting + scan rewrite
# baseline (speedup 1.0000x reference)
; __global__ void __launch_bounds__(512, 2) mk_fwd(Args args) {
;     ...
;             while (it < N_C + N_A + N_D + N_B) {
;                 int nx = 0; if (F.tid == 0) nx = 256 + (int)__hip_atomic_fetch_add(qctr, 1u, __ATOMIC_RELAXED, __HIP_MEMORY_SCOPE_AGENT);
;                 int r = it; PH_PTRS;
;                 if (r < N_C) { if (sel & 1) cprep_item(Fp, args, lp, r, P, wsp); }
;                 else if ((r -= N_C) < N_A) { if (sel & 4) { if (r < 256) gmlp_item(Fp, args, lp, r >> 2, r & 3, P, ACT); else gmlp_sample_item(Fp, args, lp, P, ACT); } }
;                 else if ((r -= N_A) < N_D) { if (sel & 2) dconv_item(Fp, args, lp, r, P, ACT + (size_t)3 * MPAD * BW); }
;                 else { r -= N_D; if (sel & 8) bprep_item(Fp, args, lp, r, P, QB, KB, VT, QS); }
.LBB0_213:
	s_cmpk_lt_i32 s26, 0x404
	s_cbranch_scc0 .Lprep_remap_hi
	s_and_b32 s0, s26, 3
	s_lshr_b32 s1, s26, 2
	s_mul_i32 s26, s0, 0x101
	s_add_i32 s26, s26, s1
	s_cmp_eq_u32 s0, 3
	s_cselect_b32 s0, 7, 0
	s_add_i32 s26, s26, s0
	s_branch .Lprep_remap_done
.Lprep_remap_hi:
	s_sub_i32 s26, s26, 0x101
